# combo12 + Resid GEMM epilogue: four of the eight second-half residual-row loads issued with the first batch into free registers (one exposed round trip less per tile)
# speedup vs baseline: 1.0021x; 1.0021x over previous
.LBB0_350:
	s_cbranch_execz .LBB0_323
	v_lshlrev_b64 v[166:167], 1, v[202:203]
	v_lshl_add_u64 v[158:159], s[26:27], 0, v[166:167]
	v_lshlrev_b64 v[168:169], 11, v[204:205]
	s_waitcnt lgkmcnt(0)
	v_lshl_add_u64 v[130:131], v[158:159], 0, v[168:169]
	global_load_dwordx4 v[172:175], v[130:131], off
	global_load_dwordx4 v[154:157], v[130:131], off offset:256
	v_lshlrev_b64 v[164:165], 11, v[210:211]
	v_lshlrev_b64 v[162:163], 11, v[208:209]
	v_lshlrev_b64 v[160:161], 11, v[206:207]
	v_lshl_add_u64 v[130:131], v[158:159], 0, v[164:165]
	v_lshl_add_u64 v[132:133], v[158:159], 0, v[162:163]
	v_lshl_add_u64 v[170:171], v[158:159], 0, v[160:161]
	global_load_dwordx4 v[150:153], v[130:131], off
	global_load_dwordx4 v[146:149], v[130:131], off offset:256
	global_load_dwordx4 v[142:145], v[132:133], off
	global_load_dwordx4 v[138:141], v[132:133], off offset:256
	global_load_dwordx4 v[134:137], v[170:171], off
	s_nop 0
	global_load_dwordx4 v[130:133], v[170:171], off offset:256
	v_add_u32_e32 v220, 0x80, v204
	v_ashrrev_i32_e32 v221, 31, v220
	v_lshlrev_b64 v[220:221], 11, v[220:221]
	v_lshl_add_u64 v[220:221], v[158:159], 0, v[220:221]
	global_load_dwordx4 v[212:215], v[220:221], off
	global_load_dwordx4 v[216:219], v[220:221], off offset:256
	v_add_u32_e32 v232, 0x90, v204
	v_ashrrev_i32_e32 v233, 31, v232
	v_lshlrev_b64 v[232:233], 11, v[232:233]
	v_lshl_add_u64 v[232:233], v[158:159], 0, v[232:233]
	global_load_dwordx4 v[224:227], v[232:233], off
	global_load_dwordx4 v[248:251], v[232:233], off offset:256
	v_cmp_lt_i32_e32 vcc, v239, v244
	v_mov_b32_e32 v195, v194
	s_lshl_b32 s30, s64, 2
	v_cndmask_b32_e32 v170, v234, v239, vcc
	v_cmp_lt_i32_e32 vcc, v240, v244
	v_lshlrev_b32_e32 v171, 2, v170
	s_ashr_i32 s31, s30, 31
	v_cndmask_b32_e32 v176, v234, v240, vcc
	v_lshlrev_b32_e32 v170, 2, v176
	s_waitcnt vmcnt(4)
	v_lshlrev_b32_e32 v178, 16, v174
	v_and_b32_e32 v179, 0xffff0000, v174
	v_lshlrev_b32_e32 v174, 16, v175
	v_and_b32_e32 v175, 0xffff0000, v175
	v_lshlrev_b32_e32 v180, 16, v154
	v_and_b32_e32 v181, 0xffff0000, v154
	v_lshlrev_b32_e32 v154, 16, v155
	v_and_b32_e32 v155, 0xffff0000, v155
	v_lshlrev_b32_e32 v182, 16, v156
	v_and_b32_e32 v183, 0xffff0000, v156
	v_lshlrev_b32_e32 v156, 16, v157
	v_and_b32_e32 v157, 0xffff0000, v157
	v_lshlrev_b32_e32 v176, 16, v172
	v_and_b32_e32 v177, 0xffff0000, v172
	v_lshlrev_b32_e32 v172, 16, v173
	v_and_b32_e32 v173, 0xffff0000, v173
	v_pk_fma_f32 v[124:125], v[194:195], v[124:125], v[174:175]
	v_pk_fma_f32 v[122:123], v[196:197], v[122:123], v[178:179]
	v_pk_fma_f32 v[120:121], v[194:195], v[120:121], v[154:155]
	v_pk_fma_f32 v[154:155], v[194:195], v[116:117], v[156:157]
	v_pk_fma_f32 v[156:157], v[196:197], v[114:115], v[182:183]
	v_pk_fma_f32 v[126:127], v[196:197], v[126:127], v[176:177]
	v_pk_fma_f32 v[128:129], v[194:195], v[128:129], v[172:173]
	v_pk_fma_f32 v[118:119], v[196:197], v[118:119], v[180:181]
	v_pk_mul_f32 v[172:173], v[122:123], v[122:123]
	v_pk_mul_f32 v[174:175], v[124:125], v[124:125]
	v_cvt_pk_bf16_f32 v116, v122, v123
	v_cvt_pk_bf16_f32 v117, v124, v125
	v_pk_mul_f32 v[122:123], v[156:157], v[156:157]
	v_pk_mul_f32 v[124:125], v[154:155], v[154:155]
	v_cvt_pk_bf16_f32 v114, v126, v127
	v_cvt_pk_bf16_f32 v115, v128, v129
	v_pk_fma_f32 v[128:129], v[128:129], v[128:129], v[174:175]
	v_pk_fma_f32 v[126:127], v[126:127], v[126:127], v[172:173]
	v_pk_fma_f32 v[124:125], v[120:121], v[120:121], v[124:125]
	v_pk_fma_f32 v[122:123], v[118:119], v[118:119], v[122:123]
	v_add_f32_e32 v126, v126, v127
	v_add_f32_e32 v127, v128, v129
	v_add_f32_e32 v122, v122, v123
	v_add_f32_e32 v123, v124, v125
	v_add_f32_e32 v124, v126, v127
	v_add_f32_e32 v122, v122, v123
	v_add_f32_e32 v124, v124, v122
	ds_bpermute_b32 v125, v171, v124
	v_lshl_add_u64 v[122:123], s[26:27], 0, v[168:169]
	v_lshl_add_u64 v[122:123], v[122:123], 0, v[166:167]
	global_store_dwordx4 v[122:123], v[114:117], off
	s_waitcnt lgkmcnt(0)
	s_nop 0
	v_add_f32_e32 v114, v124, v125
	ds_bpermute_b32 v115, v170, v114
	v_cvt_pk_bf16_f32 v116, v118, v119
	v_cvt_pk_bf16_f32 v117, v120, v121
	v_cvt_pk_bf16_f32 v118, v156, v157
	v_cvt_pk_bf16_f32 v119, v154, v155
	global_store_dwordx4 v[122:123], v[116:119], off offset:256
	s_and_saveexec_b64 s[34:35], s[6:7]
	s_cbranch_execz .LBB0_353
	v_lshlrev_b64 v[116:117], 6, v[204:205]
	v_lshl_add_u64 v[116:117], s[24:25], 0, v[116:117]
	v_lshl_add_u64 v[116:117], s[30:31], 2, v[116:117]
	s_lshl_b32 s84, s47, 2
	v_lshl_add_u64 v[116:117], v[116:117], 0, s[84:85]
	s_waitcnt lgkmcnt(0)
	v_add_f32_e32 v114, v114, v115
	global_store_dword v[116:117], v114, off

.LBB0_359:
	s_or_b64 exec, exec, s[34:35]
	v_add_u32_e32 v106, 0x80, v204
	v_ashrrev_i32_e32 v107, 31, v106
	v_lshlrev_b64 v[112:113], 11, v[106:107]
	s_waitcnt lgkmcnt(0)
	v_lshl_add_u64 v[66:67], v[158:159], 0, v[112:113]
	v_add_u32_e32 v102, 0x90, v204
	v_ashrrev_i32_e32 v103, 31, v102
	v_add_u32_e32 v98, 0xa0, v204
	v_lshlrev_b64 v[104:105], 11, v[102:103]
	v_ashrrev_i32_e32 v99, 31, v98
	v_add_u32_e32 v94, 0xb0, v204
	v_lshl_add_u64 v[66:67], v[158:159], 0, v[104:105]
	v_lshlrev_b64 v[100:101], 11, v[98:99]
	v_ashrrev_i32_e32 v95, 31, v94
	v_lshl_add_u64 v[66:67], v[158:159], 0, v[100:101]
	v_lshlrev_b64 v[96:97], 11, v[94:95]
	global_load_dwordx4 v[78:81], v[66:67], off
	global_load_dwordx4 v[70:73], v[66:67], off offset:256
	v_lshl_add_u64 v[66:67], v[158:159], 0, v[96:97]
	global_load_dwordx4 v[74:77], v[66:67], off
	s_nop 0
	global_load_dwordx4 v[66:69], v[66:67], off offset:256
	v_mov_b32_e32 v195, v194
	s_waitcnt vmcnt(4)
	v_lshlrev_b32_e32 v114, 16, v212
	v_and_b32_e32 v115, 0xffff0000, v212
	v_lshlrev_b32_e32 v108, 16, v213
	v_and_b32_e32 v109, 0xffff0000, v213
	v_lshlrev_b32_e32 v116, 16, v214
	v_and_b32_e32 v117, 0xffff0000, v214
	v_lshlrev_b32_e32 v110, 16, v215
	v_and_b32_e32 v111, 0xffff0000, v215
	v_pk_fma_f32 v[64:65], v[194:195], v[64:65], v[108:109]
	v_pk_fma_f32 v[108:109], v[194:195], v[60:61], v[110:111]
	v_pk_fma_f32 v[60:61], v[196:197], v[58:59], v[116:117]
	v_pk_fma_f32 v[62:63], v[196:197], v[62:63], v[114:115]
	v_pk_mul_f32 v[58:59], v[60:61], v[60:61]
	v_pk_mul_f32 v[110:111], v[108:109], v[108:109]
	v_pk_fma_f32 v[58:59], v[62:63], v[62:63], v[58:59]
	v_pk_fma_f32 v[110:111], v[64:65], v[64:65], v[110:111]
	v_add_f32_e32 v58, v58, v59
	v_add_f32_e32 v59, v110, v111
	v_add_f32_e32 v110, v58, v59
	v_cvt_pk_bf16_f32 v58, v62, v63
	v_lshl_add_u64 v[62:63], s[26:27], 0, v[112:113]
	v_cvt_pk_bf16_f32 v59, v64, v65
	v_cvt_pk_bf16_f32 v60, v60, v61
	v_cvt_pk_bf16_f32 v61, v108, v109
	v_lshl_add_u64 v[62:63], v[202:203], 1, v[62:63]
	global_store_dwordx4 v[62:63], v[58:61], off
	s_waitcnt vmcnt(7)
	v_lshlrev_b32_e32 v64, 16, v218
	v_and_b32_e32 v65, 0xffff0000, v218
	v_lshlrev_b32_e32 v58, 16, v216
	v_and_b32_e32 v59, 0xffff0000, v216
	v_lshlrev_b32_e32 v60, 16, v217
	v_and_b32_e32 v61, 0xffff0000, v217
	v_lshlrev_b32_e32 v90, 16, v219
	v_and_b32_e32 v91, 0xffff0000, v219
	v_pk_fma_f32 v[54:55], v[196:197], v[54:55], v[58:59]
	v_pk_fma_f32 v[58:59], v[194:195], v[52:53], v[90:91]
	v_pk_fma_f32 v[52:53], v[196:197], v[50:51], v[64:65]
	v_pk_fma_f32 v[56:57], v[194:195], v[56:57], v[60:61]
	v_pk_mul_f32 v[50:51], v[52:53], v[52:53]
	v_pk_mul_f32 v[60:61], v[58:59], v[58:59]
	v_pk_fma_f32 v[50:51], v[54:55], v[54:55], v[50:51]
	v_pk_fma_f32 v[60:61], v[56:57], v[56:57], v[60:61]
	v_add_f32_e32 v50, v50, v51
	v_add_f32_e32 v51, v60, v61
	v_add_f32_e32 v50, v50, v51
	v_add_f32_e32 v60, v110, v50
	v_cvt_pk_bf16_f32 v50, v54, v55
	v_cvt_pk_bf16_f32 v51, v56, v57
	v_cvt_pk_bf16_f32 v52, v52, v53
	v_cvt_pk_bf16_f32 v53, v58, v59
	global_store_dwordx4 v[62:63], v[50:53], off offset:256
	ds_bpermute_b32 v50, v171, v60
	s_waitcnt lgkmcnt(0)
	v_add_f32_e32 v50, v60, v50
	ds_bpermute_b32 v51, v170, v50
	s_and_saveexec_b64 s[34:35], s[6:7]
	s_cbranch_execz .LBB0_361
	v_lshlrev_b64 v[52:53], 6, v[106:107]
	v_lshl_add_u64 v[52:53], s[24:25], 0, v[52:53]
	v_lshl_add_u64 v[52:53], s[30:31], 2, v[52:53]
	s_lshl_b32 s84, s47, 2
	v_lshl_add_u64 v[52:53], v[52:53], 0, s[84:85]
	s_waitcnt lgkmcnt(0)
	v_add_f32_e32 v50, v50, v51
	global_store_dword v[52:53], v50, off
.LBB0_361:
	s_or_b64 exec, exec, s[34:35]
	s_waitcnt vmcnt(7)
	v_lshlrev_b32_e32 v50, 16, v224
	s_waitcnt lgkmcnt(0)
	v_and_b32_e32 v51, 0xffff0000, v224
	v_lshlrev_b32_e32 v54, 16, v226
	v_and_b32_e32 v55, 0xffff0000, v226
	v_lshlrev_b32_e32 v56, 16, v227
	v_and_b32_e32 v57, 0xffff0000, v227
	v_lshlrev_b32_e32 v52, 16, v225
	v_and_b32_e32 v53, 0xffff0000, v225
	v_pk_fma_f32 v[46:47], v[196:197], v[46:47], v[50:51]
	v_pk_fma_f32 v[50:51], v[194:195], v[44:45], v[56:57]
	v_pk_fma_f32 v[44:45], v[196:197], v[42:43], v[54:55]
	v_pk_fma_f32 v[48:49], v[194:195], v[48:49], v[52:53]
	v_pk_mul_f32 v[42:43], v[44:45], v[44:45]
	v_pk_mul_f32 v[52:53], v[50:51], v[50:51]
	v_pk_fma_f32 v[42:43], v[46:47], v[46:47], v[42:43]
	v_pk_fma_f32 v[52:53], v[48:49], v[48:49], v[52:53]
	v_add_f32_e32 v42, v42, v43
	v_add_f32_e32 v43, v52, v53
	v_add_f32_e32 v54, v42, v43
	v_cvt_pk_bf16_f32 v42, v46, v47
	v_cvt_pk_bf16_f32 v43, v48, v49
	v_cvt_pk_bf16_f32 v44, v44, v45
	v_cvt_pk_bf16_f32 v45, v50, v51
	s_waitcnt vmcnt(6)
	v_lshlrev_b32_e32 v46, 16, v248
	v_and_b32_e32 v47, 0xffff0000, v248
	v_lshlrev_b32_e32 v48, 16, v249
	v_and_b32_e32 v49, 0xffff0000, v249
	v_lshlrev_b32_e32 v50, 16, v250
	v_and_b32_e32 v51, 0xffff0000, v250
	v_lshlrev_b32_e32 v52, 16, v251
	v_and_b32_e32 v53, 0xffff0000, v251
	v_pk_fma_f32 v[38:39], v[196:197], v[38:39], v[46:47]
	v_pk_fma_f32 v[40:41], v[194:195], v[40:41], v[48:49]
	v_pk_fma_f32 v[46:47], v[194:195], v[36:37], v[52:53]
	v_pk_fma_f32 v[48:49], v[196:197], v[34:35], v[50:51]
	v_pk_mul_f32 v[36:37], v[46:47], v[46:47]
	v_pk_mul_f32 v[34:35], v[48:49], v[48:49]
	v_pk_fma_f32 v[36:37], v[40:41], v[40:41], v[36:37]
	v_pk_fma_f32 v[34:35], v[38:39], v[38:39], v[34:35]
	s_nop 0
	v_add_f32_e32 v34, v34, v35
	v_add_f32_e32 v35, v36, v37
	v_add_f32_e32 v34, v34, v35
	v_add_f32_e32 v37, v54, v34
	ds_bpermute_b32 v52, v171, v37
	v_lshl_add_u64 v[34:35], s[26:27], 0, v[104:105]
	v_lshl_add_u64 v[50:51], v[202:203], 1, v[34:35]
	v_cvt_pk_bf16_f32 v36, v38, v39
	v_cvt_pk_bf16_f32 v38, v48, v49
	s_waitcnt lgkmcnt(0)
	v_add_f32_e32 v34, v37, v52
	ds_bpermute_b32 v35, v170, v34
	v_cvt_pk_bf16_f32 v37, v40, v41
	v_cvt_pk_bf16_f32 v39, v46, v47
	global_store_dwordx4 v[50:51], v[42:45], off
	global_store_dwordx4 v[50:51], v[36:39], off offset:256
	s_and_saveexec_b64 s[34:35], s[6:7]
	s_cbranch_execz .LBB0_363
	v_lshlrev_b64 v[36:37], 6, v[102:103]
	v_lshl_add_u64 v[36:37], s[24:25], 0, v[36:37]
	v_lshl_add_u64 v[36:37], s[30:31], 2, v[36:37]
	s_lshl_b32 s84, s47, 2
	v_lshl_add_u64 v[36:37], v[36:37], 0, s[84:85]
	s_waitcnt lgkmcnt(0)
	v_add_f32_e32 v34, v34, v35
	global_store_dword v[36:37], v34, off
